# A + P3 scoring per-tile set-up loads issued together (one exposed round trip instead of two)
# speedup vs baseline: 1.0026x; 1.0026x over previous
; #define LAS __attribute__((address_space(3)))
; __device__ __forceinline__ void idx_scores8(const Params& p, LAS unsigned char* buf, int b, int c, int s8, int pw, int lane, int nw) {
;     ...
;     bf16x8 af[2][4]; hp2_t wv[2][2][4];
; #pragma unroll
;     for (int rb = 0; rb < 2; ++rb) { const bf16* src = proj + (q0 + rb * 4 + ql) * NPROJ + PC_QI + head * 64 + 32 * h;
; #pragma unroll
;         for (int s = 0; s < 4; ++s) af[rb][s] = *(const bf16x8*)(src + 8 * s);
; #pragma unroll
;         for (int e = 0; e < 2; ++e) { const float* wsrc = wis + (q0 + rb * 4 + 2 * h + e) * 8; const f32x4 w0 = *(const f32x4*)wsrc, w1 = *(const f32x4*)(wsrc + 4);
; #pragma unroll
;             for (int i = 0; i < 2; ++i) { wv[rb][e][i] = (hp2_t){(_Float16)w0[2 * i], (_Float16)w0[2 * i + 1]}; wv[rb][e][2 + i] = (hp2_t){(_Float16)w1[2 * i], (_Float16)w1[2 * i + 1]}; } } }
;     const int nct = S / 32;
;     const bf16* kbase = kir + rowbase * 64 + (4 * h * 32 + r) * 8;
;     LAS unsigned char* rowq = buf + (2 * h) * 8192;
;     bf16x8 bcur[4];
; #pragma unroll
;     for (int s = 0; s < 4; ++s) bcur[s] = *(const bf16x8*)(kbase + (size_t)pw * 2048 + 256 * s);
.LBB0_3687:
	s_and_b64 vcc, exec, s[0:1]
	s_cbranch_vccz .LBB0_3693
	s_cmp_eq_u32 s84, 16
	s_cbranch_scc1 .LBB0_3693
	s_cmp_lt_u32 s84, 8
	s_cselect_b32 s1, s40, s46
	s_cmp_lt_u32 s1, 4
	s_cbranch_scc1 .LBB0_3693
	s_lshl_b32 s0, s1, 5
	s_add_i32 s4, s0, 64
	s_add_i32 s0, s4, s0
	s_lshr_b32 s0, s0, 5
	v_readlane_b32 s6, v242, 51
	s_cmp_ge_u32 s6, s0
	v_readlane_b32 s7, v242, 52
	s_cbranch_scc1 .LBB0_3693
	s_lshl_b32 s5, s84, 3
	s_lshl_b32 s1, s1, 6
	s_and_b32 s5, s5, 56
	s_or_b32 s1, s1, s5
	v_readlane_b32 s12, v241, 23
	s_or_b32 s6, s12, s1
	v_or_b32_e32 v0, s6, v80
	s_waitcnt vmcnt(0)
	v_mov_b64_e32 v[16:17], s[82:83]
	s_movk_i32 s7, 0x2a00
	v_readlane_b32 s13, v241, 24
	s_and_b32 s1, s4, 0xfc0
	v_mad_u64_u32 v[0:1], s[4:5], v0, s7, v[16:17]
	v_mad_i32_i24 v1, s13, v114, v1
	v_lshl_add_u64 v[0:1], v[0:1], 0, v[78:79]
	v_mov_b32_e32 v89, v79
	v_lshl_add_u64 v[0:1], v[0:1], 0, v[88:89]
	s_mov_b64 s[14:15], 0x2001400
	s_mov_b32 s12, 0x2001000
	v_lshl_add_u64 v[2:3], v[0:1], 0, s[14:15]
	v_add_co_u32_e32 v0, vcc, s12, v0
	v_readlane_b32 s10, v242, 55
	s_nop 0
	v_addc_co_u32_e32 v1, vcc, 0, v1, vcc
	global_load_dwordx4 v[32:35], v[0:1], off offset:1024
	global_load_dwordx4 v[36:39], v[2:3], off offset:16
	global_load_dwordx4 v[40:43], v[2:3], off offset:32
	global_load_dwordx4 v[44:47], v[2:3], off offset:48
	v_mov_b32_e32 v1, s13
	v_or_b32_e32 v0, s6, v82
	v_lshlrev_b64 v[0:1], 5, v[0:1]
	v_readlane_b32 s11, v242, 56
	s_or_b32 s6, s6, 4
	s_nop 0
	v_lshl_add_u64 v[12:13], s[10:11], 0, v[0:1]
	global_load_dwordx4 v[0:3], v[12:13], off offset:48
	global_load_dwordx4 v[4:7], v[12:13], off offset:32
	global_load_dwordx4 v[8:11], v[12:13], off offset:16
	s_nop 0
	global_load_dwordx4 v[12:15], v[12:13], off
	v_or_b32_e32 v160, s6, v80
	v_mad_u64_u32 v[160:161], s[4:5], v160, s7, v[16:17]
	v_mad_i32_i24 v161, s13, v114, v161
	v_lshl_add_u64 v[160:161], v[160:161], 0, v[78:79]
	v_lshl_add_u64 v[160:161], v[160:161], 0, v[88:89]
	v_lshl_add_u64 v[162:163], v[160:161], 0, s[14:15]
	v_add_co_u32_e32 v160, vcc, s12, v160
	s_nop 1
	v_addc_co_u32_e32 v161, vcc, 0, v161, vcc
	global_load_dwordx4 v[48:51], v[160:161], off offset:1024
	global_load_dwordx4 v[52:55], v[162:163], off offset:16
	global_load_dwordx4 v[56:59], v[162:163], off offset:32
	global_load_dwordx4 v[60:63], v[162:163], off offset:48
	v_mov_b32_e32 v161, s13
	v_or_b32_e32 v160, s6, v82
	v_lshlrev_b64 v[160:161], 5, v[160:161]
	v_lshl_add_u64 v[164:165], s[10:11], 0, v[160:161]
	global_load_dwordx4 v[144:147], v[164:165], off offset:48
	global_load_dwordx4 v[148:151], v[164:165], off offset:32
	global_load_dwordx4 v[152:155], v[164:165], off offset:16
	global_load_dwordx4 v[156:159], v[164:165], off
	global_load_dwordx4 v[64:67], v[94:95], off offset:1536
	global_load_dwordx4 v[68:71], v[94:95], off offset:1024
	global_load_dwordx4 v[72:75], v[94:95], off offset:512
	global_load_dwordx4 v[16:19], v[94:95], off
	v_readlane_b32 s6, v242, 51
	v_readlane_b32 s4, v242, 58
	s_mov_b32 s5, s6
	v_readlane_b32 s7, v242, 52
	s_waitcnt vmcnt(12)
	v_cvt_pk_f16_f32 v121, v0, v1
	v_cvt_pk_f16_f32 v123, v2, v3
	v_cvt_pk_f16_f32 v116, v12, v13
	v_cvt_pk_f16_f32 v117, v8, v9
	v_cvt_pk_f16_f32 v118, v14, v15
	v_cvt_pk_f16_f32 v119, v10, v11
	v_cvt_pk_f16_f32 v120, v4, v5
	v_cvt_pk_f16_f32 v122, v6, v7
	s_waitcnt vmcnt(4)
	v_cvt_pk_f16_f32 v128, v144, v145
	v_cvt_pk_f16_f32 v124, v152, v153
	v_cvt_pk_f16_f32 v89, v156, v157
	v_cvt_pk_f16_f32 v125, v158, v159
	v_cvt_pk_f16_f32 v126, v154, v155
	v_cvt_pk_f16_f32 v127, v148, v149
	v_cvt_pk_f16_f32 v129, v150, v151
	v_cvt_pk_f16_f32 v130, v146, v147
	v_cndmask_b32_e64 v0, 0, 1, s[2:3]
	s_nop 0
	v_lshl_add_u32 v131, v0, 16, v112
